# ds_read2_b64 split into two ds_read_b64 (full-rate LDS reads) in DeltaNet steps C2/D and the attention k-loop, lgkmcnt re-derived
# speedup vs baseline: 1.0075x; 1.0070x over previous
.LBB0_705:
	v_mov_b32_e32 v0, s60
	v_cndmask_b32_e64 v155, v111, v0, s[6:7]
	s_add_i32 s18, 16, 0x21000
	s_add_i32 s19, 16, 0x8800
	v_mov_b32_e32 v3, v120
	v_mov_b32_e32 v0, v107
	v_mov_b32_e32 v74, v121
	s_and_b64 s[0:1], s[14:15], exec
	s_waitcnt lgkmcnt(0)
	s_barrier
	s_cselect_b32 s0, s19, s18
	v_mul_lo_u32 v0, v3, s24
	s_add_i32 s1, 16, 0x16400
	v_lshlrev_b32_e32 v68, 3, v74
	v_add3_u32 v0, s1, v0, v68
	v_add_u32_e32 v1, 0x1000, v0
	v_mul_lo_u32 v69, v3, 40
	v_lshl_add_u32 v3, v3, 1, s43
	v_mul_lo_u32 v74, v74, s25
	ds_read_b64 v[64:65], v1 offset:512
	ds_read_b64 v[66:67], v1 offset:544
	v_add_u32_e32 v1, 0x1800, v0
	v_add3_u32 v68, s40, v68, v69
	v_add_u32_e32 v156, v3, v74
	ds_read_b64 v[72:73], v0 offset:2304
	ds_read_b64 v[60:61], v1 offset:768
	ds_read_b64 v[62:63], v1 offset:800
	ds_read_b64 v[0:1], v0 offset:6976
	ds_read_b64 v[84:85], v68
	ds_read_b64 v[86:87], v68 offset:640
	ds_read_b64 v[70:71], v68 offset:1920
	ds_read_b64 v[68:69], v68 offset:1280
	ds_read_u16 v188, v156 offset:61696
	v_add_u32_e32 v75, 0xd000, v3
	v_add_u32_e32 v101, 0x6510, v74
	v_add_u32_e32 v162, v75, v101
	ds_read_u16 v77, v162
	ds_read_u16 v189, v156 offset:62224
	v_add_u32_e32 v102, 0x6720, v74
	v_add_u32_e32 v163, v75, v102
	ds_read_u16 v78, v163
	v_add_u32_e32 v100, 0x6300, v74
	ds_read_u16 v190, v156 offset:62752
	v_add_u32_e32 v96, 0x4200, v74
	v_add_u32_e32 v97, 0x4410, v74
	v_add_u32_e32 v98, 0x4620, v74
	v_add_u32_e32 v99, 0x4830, v74
	v_add_u32_e32 v74, 0x6930, v74
	v_add_u32_e32 v164, v75, v74
	v_add_u32_e32 v157, v75, v96
	v_add_u32_e32 v158, v75, v97
	v_add_u32_e32 v159, v75, v98
	v_add_u32_e32 v160, v75, v99
	v_add_u32_e32 v161, v75, v100
	ds_read_u16 v192, v164
	ds_read_u16 v191, v156 offset:63280
	v_add_u32_e32 v75, 0xd020, v3
	ds_read_u16 v193, v157
	v_add_u32_e32 v181, v75, v97
	v_add_u32_e32 v185, v75, v101
	v_add_u32_e32 v182, v75, v98
	v_add_u32_e32 v186, v75, v102
	ds_read_u16 v194, v158
	v_add_u32_e32 v180, v75, v96
	v_add_u32_e32 v183, v75, v99
	v_add_u32_e32 v184, v75, v100
	v_add_u32_e32 v187, v75, v74
	ds_read_u16 v195, v159
	ds_read_u16 v196, v160
	ds_read_u16 v76, v161
	s_waitcnt lgkmcnt(1)
	v_lshlrev_b32_e32 v88, 16, v188
	v_lshlrev_b32_e32 v89, 16, v189
	v_lshlrev_b32_e32 v90, 16, v190
	v_lshlrev_b32_e32 v77, 16, v77
	v_lshlrev_b32_e32 v78, 16, v78
	v_lshlrev_b32_e32 v79, 16, v192
	v_lshlrev_b32_e32 v91, 16, v191
	v_lshlrev_b32_e32 v80, 16, v193
	v_lshlrev_b32_e32 v81, 16, v194
	v_lshlrev_b32_e32 v82, 16, v195
	v_lshlrev_b32_e32 v83, 16, v196
	ds_read_u16 v168, v156 offset:53248
	ds_read_u16 v3, v156 offset:53280
	ds_read_u16 v92, v156 offset:53808
	ds_read_u16 v93, v156 offset:62256
	ds_read_u16 v97, v181
	ds_read_u16 v101, v185
	ds_read_u16 v94, v156 offset:62784
	ds_read_u16 v98, v182
	ds_read_u16 v102, v186
	s_waitcnt lgkmcnt(6)
	v_lshlrev_b32_e32 v165, 16, v92
	ds_read_u16 v92, v156 offset:54336
	ds_read_u16 v95, v156 offset:63312
	ds_read_u16 v99, v183
	ds_read_u16 v74, v187
	ds_read_u16 v96, v180
	ds_read_u16 v100, v184
	s_waitcnt lgkmcnt(5)
	v_lshlrev_b32_e32 v166, 16, v92
	ds_read_u16 v92, v156 offset:54864
	v_lshlrev_b32_e32 v3, 16, v3
	v_lshlrev_b32_e32 v76, 16, v76
	v_lshlrev_b32_e32 v93, 16, v93
	v_lshlrev_b32_e32 v94, 16, v94
	s_waitcnt lgkmcnt(0)
	v_lshlrev_b32_e32 v167, 16, v92
	ds_read_u16 v92, v156 offset:61728
	ds_read_u16 v169, v156 offset:54832
	ds_read_u16 v170, v156 offset:53776
	ds_read_u16 v171, v156 offset:54304
	v_lshlrev_b32_e32 v95, 16, v95
	v_lshlrev_b32_e32 v96, 16, v96
	v_lshlrev_b32_e32 v97, 16, v97
	s_waitcnt lgkmcnt(3)
	v_lshlrev_b32_e32 v92, 16, v92
	v_lshlrev_b32_e32 v98, 16, v98
	v_lshlrev_b32_e32 v99, 16, v99
	v_lshlrev_b32_e32 v100, 16, v100
	v_lshlrev_b32_e32 v101, 16, v101
	v_lshlrev_b32_e32 v102, 16, v102
	v_lshlrev_b32_e32 v103, 16, v74
	v_mov_b32_e32 v140, v84
	v_mov_b32_e32 v141, v85
	v_mov_b32_e32 v142, v2
	v_mov_b32_e32 v143, v2
	s_waitcnt lgkmcnt(2)
	v_lshlrev_b32_e32 v84, 16, v169
	v_lshlrev_b32_e32 v85, 16, v168
	s_waitcnt lgkmcnt(1)
	v_lshlrev_b32_e32 v168, 16, v170
	s_waitcnt lgkmcnt(0)
	v_lshlrev_b32_e32 v169, 16, v171
	v_cvt_pk_bf16_f32 v169, v169, v84
	v_cvt_pk_bf16_f32 v168, v85, v168
	v_mov_b32_e32 v170, v2
	v_mov_b32_e32 v171, v2
	v_mov_b32_e32 v74, v2
	v_mov_b32_e32 v75, v2
	v_mfma_f32_16x16x32_bf16 v[168:171], v[140:143], v[168:171], 0
	v_cvt_pk_bf16_f32 v173, v166, v167
	v_cvt_pk_bf16_f32 v172, v3, v165
	v_mov_b32_e32 v174, v2
	v_mov_b32_e32 v175, v2
	v_mov_b32_e32 v84, v86
	v_mov_b32_e32 v85, v87
	v_mfma_f32_16x16x32_bf16 v[140:143], v[140:143], v[172:175], 0
	s_nop 0
	v_cvt_pk_bf16_f32 v173, v170, v171
	v_cvt_pk_bf16_f32 v172, v168, v169
	v_mov_b32_e32 v86, v2
	v_mov_b32_e32 v87, v2
	v_mfma_f32_16x16x32_bf16 v[88:91], v[72:75], v[172:175], v[88:91]
	v_mov_b32_e32 v176, v2
	v_mov_b32_e32 v177, v2
	v_mov_b32_e32 v178, v2
	v_mov_b32_e32 v179, v2
	v_mov_b32_e32 v3, v2
	s_nop 2
	v_cvt_pk_bf16_f32 v175, v90, v91
	v_cvt_pk_bf16_f32 v174, v88, v89
	s_cmp_lg_u32 16, -1
	s_cselect_b32 s1, s41, 0
	v_mfma_f32_16x16x32_bf16 v[88:91], v[84:87], v[174:177], 0
	v_cvt_pk_bf16_f32 v177, v142, v143
	v_cvt_pk_bf16_f32 v176, v140, v141
	s_nop 1
	v_mfma_f32_16x16x32_bf16 v[72:75], v[72:75], v[176:179], v[92:95]
	s_nop 2
	v_cvt_pk_bf16_f32 v175, v90, v91
	v_cvt_pk_bf16_f32 v174, v88, v89
	v_mov_b32_e32 v94, v2
	v_mov_b32_e32 v95, v2
	s_nop 0
	v_cvt_pk_bf16_f32 v93, v74, v75
	v_cvt_pk_bf16_f32 v92, v72, v73
	v_mfma_f32_16x16x32_bf16 v[80:83], v[64:67], v[172:175], v[80:83]
	s_nop 0
	v_mfma_f32_16x16x32_bf16 v[72:75], v[84:87], v[92:95], 0
	v_mov_b32_e32 v84, v68
	v_mov_b32_e32 v85, v69
	s_nop 3
	v_cvt_pk_bf16_f32 v93, v82, v83
	v_cvt_pk_bf16_f32 v92, v80, v81
	v_mfma_f32_16x16x32_bf16 v[76:79], v[60:63], v[172:175], v[76:79]
	v_cvt_pk_bf16_f32 v179, v74, v75
	v_cvt_pk_bf16_f32 v178, v72, v73
	v_mov_b32_e32 v68, v2
	v_mfma_f32_16x16x32_bf16 v[80:83], v[84:87], v[92:95], 0
	v_mov_b32_e32 v69, v2
	v_mfma_f32_16x16x32_bf16 v[64:67], v[64:67], v[176:179], v[96:99]
	v_mfma_f32_16x16x32_bf16 v[60:63], v[60:63], v[176:179], v[100:103]
	s_nop 6
	v_cvt_pk_bf16_f32 v67, v66, v67
	v_cvt_pk_bf16_f32 v66, v64, v65
	s_nop 1
	v_mfma_f32_16x16x32_bf16 v[64:67], v[84:87], v[66:69], 0
	v_cvt_pk_bf16_f32 v85, v82, v83
	v_cvt_pk_bf16_f32 v84, v80, v81
	v_mov_b32_e32 v68, v70
	v_mov_b32_e32 v69, v71
	v_mov_b32_e32 v70, v2
	v_mov_b32_e32 v71, v2
	v_mfma_f32_16x16x32_bf16 v[76:79], v[0:3], v[84:87], v[76:79]
	s_nop 7
	v_cvt_pk_bf16_f32 v85, v78, v79
	v_cvt_pk_bf16_f32 v84, v76, v77
	s_nop 1
	v_mfma_f32_16x16x32_bf16 v[76:79], v[68:71], v[84:87], 0
	v_cvt_pk_bf16_f32 v85, v66, v67
	v_cvt_pk_bf16_f32 v84, v64, v65
	s_nop 1
	v_mfma_f32_16x16x32_bf16 v[60:63], v[0:3], v[84:87], v[60:63]
	v_cvt_pk_bf16_f32 v87, v30, v31
	v_cvt_pk_bf16_f32 v86, v28, v29
	v_cvt_pk_bf16_f32 v85, v34, v35
	v_cvt_pk_bf16_f32 v84, v32, v33
	s_nop 3
	v_cvt_pk_bf16_f32 v1, v62, v63
	v_cvt_pk_bf16_f32 v0, v60, v61
	s_nop 1
	v_mfma_f32_16x16x32_bf16 v[60:63], v[68:71], v[0:3], 0
	v_cvt_pk_bf16_f32 v0, v168, s0
	ds_write_b16 v156, v0 offset:53248
	v_cvt_pk_bf16_f32 v0, v169, s0
	ds_write_b16 v156, v0 offset:53776
	v_cvt_pk_bf16_f32 v0, v170, s0
	ds_write_b16 v156, v0 offset:54304
	v_cvt_pk_bf16_f32 v0, v171, s0
	ds_write_b16 v156, v0 offset:54832
	v_cvt_pk_bf16_f32 v0, v88, s0
	ds_write_b16 v156, v0 offset:61696
	v_cvt_pk_bf16_f32 v0, v89, s0
	ds_write_b16 v156, v0 offset:62224
	v_cvt_pk_bf16_f32 v0, v90, s0
	ds_write_b16 v156, v0 offset:62752
	v_cvt_pk_bf16_f32 v0, v91, s0
	ds_write_b16 v156, v0 offset:63280
	v_cvt_pk_bf16_f32 v0, v80, s0
	ds_write_b16 v157, v0
	v_cvt_pk_bf16_f32 v0, v81, s0
	ds_write_b16 v158, v0
	v_cvt_pk_bf16_f32 v0, v82, s0
	ds_write_b16 v159, v0
	v_cvt_pk_bf16_f32 v0, v83, s0
	ds_write_b16 v160, v0
	v_cvt_pk_bf16_f32 v0, v76, s0
	ds_write_b16 v161, v0
	v_cvt_pk_bf16_f32 v0, v77, s0
	ds_write_b16 v162, v0
	v_cvt_pk_bf16_f32 v0, v78, s0
	ds_write_b16 v163, v0
	v_cvt_pk_bf16_f32 v0, v79, s0
	ds_write_b16 v164, v0
	v_cvt_pk_bf16_f32 v0, v140, s0
	ds_write_b16 v156, v0 offset:53280
	v_cvt_pk_bf16_f32 v0, v141, s0
	ds_write_b16 v156, v0 offset:53808
	v_cvt_pk_bf16_f32 v0, v142, s0
	ds_write_b16 v156, v0 offset:54336
	v_cvt_pk_bf16_f32 v0, v143, s0
	ds_write_b16 v156, v0 offset:54864
	v_cvt_pk_bf16_f32 v0, v72, s0
	ds_write_b16 v156, v0 offset:61728
	v_cvt_pk_bf16_f32 v0, v73, s0
	ds_write_b16 v156, v0 offset:62256
	v_cvt_pk_bf16_f32 v0, v74, s0
	ds_write_b16 v156, v0 offset:62784
	v_cvt_pk_bf16_f32 v0, v75, s0
	ds_write_b16 v156, v0 offset:63312
	v_cvt_pk_bf16_f32 v0, v64, s0
	ds_write_b16 v180, v0
	v_cvt_pk_bf16_f32 v0, v65, s0
	ds_write_b16 v181, v0
	v_cvt_pk_bf16_f32 v0, v66, s0
	ds_write_b16 v182, v0
	v_cvt_pk_bf16_f32 v0, v67, s0
	ds_write_b16 v183, v0
	v_cvt_pk_bf16_f32 v0, v60, s0
	ds_write_b16 v184, v0
	v_cvt_pk_bf16_f32 v0, v61, s0
	ds_write_b16 v185, v0
	v_cvt_pk_bf16_f32 v0, v62, s0
	ds_write_b16 v186, v0
	v_cvt_pk_bf16_f32 v0, v63, s0
	v_mov_b32_e32 v3, v107
	v_mov_b32_e32 v88, v120
	v_mov_b32_e32 v89, v121
	ds_write_b16 v187, v0
	s_waitcnt lgkmcnt(0)
	s_barrier
	v_cvt_pk_bf16_f32 v63, v6, v7
	v_mul_lo_u32 v0, v88, s22
	v_lshlrev_b32_e32 v90, 3, v89
	v_add3_u32 v164, 16, v0, v90
	v_add_u32_e32 v0, 0xd000, v164
	ds_read_b64 v[72:73], v0 offset:256
	ds_read_b64 v[74:75], v0 offset:288
	ds_read_b64 v[76:77], v0 offset:320
	ds_read_b64 v[78:79], v0 offset:352
	v_cvt_pk_bf16_f32 v62, v4, v5
	v_cvt_pk_bf16_f32 v61, v10, v11
	v_cvt_pk_bf16_f32 v60, v8, v9
	ds_read_b64 v[80:81], v0 offset:384
	ds_read_b64 v[82:83], v0 offset:416
	v_cvt_pk_bf16_f32 v67, v14, v15
	s_waitcnt lgkmcnt(4)
	v_mfma_f32_16x16x32_bf16 v[72:75], v[72:75], v[60:63], 0
	v_cvt_pk_bf16_f32 v66, v12, v13
	v_cvt_pk_bf16_f32 v65, v18, v19
	v_cvt_pk_bf16_f32 v64, v16, v17
	ds_read_b64 v[92:93], v0 offset:448
	ds_read_b64 v[94:95], v0 offset:480
	v_mul_lo_u32 v0, v88, s21
	s_waitcnt lgkmcnt(4)
	v_mfma_f32_16x16x32_bf16 v[72:75], v[76:79], v[64:67], v[72:75]
	v_cvt_pk_bf16_f32 v71, v22, v23
	v_cvt_pk_bf16_f32 v70, v20, v21
	v_cvt_pk_bf16_f32 v69, v26, v27
	v_cvt_pk_bf16_f32 v68, v24, v25
	v_add3_u32 v165, s66, v90, v0
	ds_read_b64 v[76:77], v165
	ds_read_b64 v[78:79], v165 offset:32
	s_waitcnt lgkmcnt(4)
	v_mfma_f32_16x16x32_bf16 v[72:75], v[80:83], v[68:71], v[72:75]
	v_add_u32_e32 v1, 0xf000, v164
	ds_read_b64 v[98:99], v1 offset:640
	ds_read_b64 v[100:101], v1 offset:672
	v_add_u32_e32 v91, 0x1000, v165
	s_waitcnt lgkmcnt(4)
	v_mfma_f32_16x16x32_bf16 v[80:83], v[92:95], v[84:87], v[72:75]
	ds_read_b64 v[92:93], v165 offset:128
	ds_read_b64 v[94:95], v165 offset:160
	v_lshl_add_u32 v0, v88, 1, s61
	v_mad_u64_u32 v[102:103], s[12:13], v89, s25, v[0:1]
	ds_read_b64 v[72:73], v165 offset:64
	ds_read_b64 v[74:75], v165 offset:96
	s_waitcnt lgkmcnt(6)
	v_mfma_f32_16x16x32_bf16 v[76:79], v[76:79], v[60:63], 0
	s_waitcnt lgkmcnt(0)
	v_mfma_f32_16x16x32_bf16 v[72:75], v[72:75], v[64:67], v[76:79]
	s_nop 5
	ds_read_b64 v[76:77], v165 offset:192
	ds_read_b64 v[78:79], v165 offset:224
	v_mfma_f32_16x16x32_bf16 v[72:75], v[92:95], v[68:71], v[72:75]
	ds_read_b64 v[94:95], v1 offset:512
	ds_read_b64 v[96:97], v1 offset:544
	v_lshlrev_b32_e32 v92, 2, v89
	v_or_b32_e32 v176, 1, v92
	s_waitcnt lgkmcnt(2)
	v_mfma_f32_16x16x32_bf16 v[72:75], v[76:79], v[84:87], v[72:75]
	ds_read_b64 v[76:77], v1 offset:576
	ds_read_b64 v[78:79], v1 offset:608
	v_mad_u64_u32 v[160:161], s[12:13], v176, s22, v[0:1]
	s_waitcnt lgkmcnt(2)
	v_mfma_f32_16x16x32_bf16 v[94:97], v[94:97], v[60:63], 0
	v_add_u32_e32 v172, 0x1ef0, v160
	s_cselect_b32 s12, 16, 0
	s_add_u32 s12, s12, 0x1c8fc
	s_waitcnt lgkmcnt(0)
	v_mfma_f32_16x16x32_bf16 v[76:79], v[76:79], v[64:67], v[94:97]
	s_addc_u32 s13, s1, 0
	s_nop 1
	ds_read_b64 v[94:95], v91 offset:256
	ds_read_b64 v[96:97], v91 offset:288
	s_cmp_lg_u64 s[12:13], 0
	v_mfma_f32_16x16x32_bf16 v[76:79], v[98:101], v[68:71], v[76:79]
	ds_read_b64 v[98:99], v1 offset:704
	ds_read_b64 v[100:101], v1 offset:736
	ds_read_u16 v0, v102 offset:53248
	ds_read_u16 v1, v160 offset:53248
	ds_read_u16 v93, v160 offset:53776
	ds_read_u16 v102, v160 offset:54304
	ds_read_u16 v161, v160 offset:61168
	ds_read_u16 v162, v160 offset:61696
	ds_read_u16 v166, v160 offset:62224
	ds_read_u16 v167, v160 offset:62752
	ds_read_b64 v[140:141], v91 offset:320
	ds_read_b64 v[142:143], v91 offset:352
	s_waitcnt lgkmcnt(8)
	v_lshlrev_b32_e32 v1, 16, v1
	v_mfma_f32_16x16x32_bf16 v[94:97], v[94:97], v[60:63], 0
	v_lshlrev_b32_e32 v0, 16, v0
	v_pk_add_f32 v[0:1], v[0:1], v[80:81] neg_lo:[0,1] neg_hi:[0,1]
	v_add_u32_e32 v80, 0x4200, v164
	v_mfma_f32_16x16x32_bf16 v[98:101], v[98:101], v[84:87], v[76:79]
	v_add_u32_e32 v168, 0xd000, v80
	s_waitcnt lgkmcnt(6)
	v_lshlrev_b32_e32 v81, 16, v102
	ds_read_b64 v[156:157], v91 offset:448
	ds_read_b64 v[158:159], v91 offset:480
	ds_read_b64 v[76:77], v91 offset:384
	ds_read_b64 v[78:79], v91 offset:416
	s_waitcnt lgkmcnt(4)
	v_mfma_f32_16x16x32_bf16 v[94:97], v[140:143], v[64:67], v[94:97]
	ds_read_b64 v[140:141], v168 offset:256
	ds_read_b64 v[142:143], v168 offset:288
	v_lshlrev_b32_e32 v80, 16, v93
	v_pk_add_f32 v[102:103], v[80:81], v[82:83] neg_lo:[0,1] neg_hi:[0,1]
	ds_read_b64 v[80:81], v168 offset:320
	ds_read_b64 v[82:83], v168 offset:352
	s_waitcnt lgkmcnt(4)
	v_mfma_f32_16x16x32_bf16 v[76:79], v[76:79], v[68:71], v[94:97]
	s_nop 2
	ds_read_b64 v[94:95], v168 offset:384
	ds_read_b64 v[96:97], v168 offset:416
	v_add_u32_e32 v93, 0x2000, v165
	v_lshlrev_b32_e32 v163, 16, v162
	s_waitcnt lgkmcnt(4)
	v_mfma_f32_16x16x32_bf16 v[140:143], v[140:143], v[60:63], 0
	v_lshlrev_b32_e32 v162, 16, v161
	v_add_u32_e32 v165, 0x3000, v165
	s_cselect_b32 s1, s12, -1
	v_mfma_f32_16x16x32_bf16 v[76:79], v[156:159], v[84:87], v[76:79]
	ds_read_b64 v[156:157], v168 offset:448
	ds_read_b64 v[158:159], v168 offset:480
	v_pk_add_f32 v[168:169], v[162:163], v[98:99] neg_lo:[0,1] neg_hi:[0,1]
	v_lshlrev_b32_e32 v99, 16, v167
	s_waitcnt lgkmcnt(4)
	v_mfma_f32_16x16x32_bf16 v[80:83], v[80:83], v[64:67], v[140:143]
	v_lshlrev_b32_e32 v98, 16, v166
	v_pk_add_f32 v[170:171], v[98:99], v[100:101] neg_lo:[0,1] neg_hi:[0,1]
	ds_read_b64 v[98:99], v93 offset:704
	ds_read_b64 v[100:101], v93 offset:736
	ds_read_b64 v[140:141], v93 offset:512
	ds_read_b64 v[142:143], v93 offset:544
	s_waitcnt lgkmcnt(6)
	v_mfma_f32_16x16x32_bf16 v[80:83], v[94:97], v[68:71], v[80:83]
	ds_read_b64 v[94:95], v93 offset:576
	ds_read_b64 v[96:97], v93 offset:608
	s_add_i32 s66, 16, 0x258fc
	s_and_b64 s[12:13], s[14:15], exec
	s_waitcnt lgkmcnt(6)
	v_mfma_f32_16x16x32_bf16 v[156:159], v[156:159], v[84:87], v[80:83]
	s_cselect_b32 s1, s1, s66
	v_or_b32_e32 v177, 2, v92
	v_or_b32_e32 v178, 3, v92
	ds_read_b64 v[80:81], v93 offset:640
	ds_read_b64 v[82:83], v93 offset:672
	s_waitcnt lgkmcnt(4)
	v_mfma_f32_16x16x32_bf16 v[140:143], v[140:143], v[60:63], 0
	v_add_u32_e32 v91, 16, v92
	v_add_u32_e32 v179, 17, v92
	v_add_u32_e32 v180, 18, v92
	s_waitcnt lgkmcnt(2)
	v_mfma_f32_16x16x32_bf16 v[94:97], v[94:97], v[64:67], v[140:143]
	v_add_u32_e32 v181, 19, v92
	v_add_u32_e32 v93, 32, v92
	v_add_u32_e32 v182, 33, v92
	s_waitcnt lgkmcnt(0)
	v_mfma_f32_16x16x32_bf16 v[80:83], v[80:83], v[68:71], v[94:97]
	v_add_u32_e32 v140, 0x3ff0, v160
	v_add_u32_e32 v187, 34, v92
	v_add_u32_e32 v188, 35, v92
	v_add_u32_e32 v94, 0x6300, v164
	v_add_u32_e32 v162, 0xd000, v94
	ds_read_b64 v[94:95], v162 offset:256
	ds_read_b64 v[96:97], v162 offset:288
	ds_read_u16 v160, v172 offset:61696
	ds_read_u16 v141, v172 offset:62224
	ds_read_u16 v164, v172 offset:62752
	ds_read_u16 v166, v172 offset:63280
	ds_read_u16 v183, v140 offset:61696
	ds_read_u16 v184, v140 offset:62224
	ds_read_u16 v185, v140 offset:62752
	ds_read_u16 v186, v140 offset:63280
	s_waitcnt lgkmcnt(6)
	v_lshlrev_b32_e32 v161, 16, v141
	ds_read_b64 v[140:141], v162 offset:320
	ds_read_b64 v[142:143], v162 offset:352
	v_mfma_f32_16x16x32_bf16 v[80:83], v[98:101], v[84:87], v[80:83]
	ds_read_b64 v[98:99], v162 offset:384
	ds_read_b64 v[100:101], v162 offset:416
	v_lshlrev_b32_e32 v160, 16, v160
	v_pk_add_f32 v[172:173], v[160:161], v[156:157] neg_lo:[0,1] neg_hi:[0,1]
	v_mfma_f32_16x16x32_bf16 v[94:97], v[94:97], v[60:63], 0
	ds_read_b64 v[160:161], v162 offset:448
	ds_read_b64 v[162:163], v162 offset:480
	s_waitcnt lgkmcnt(10)
	v_lshlrev_b32_e32 v157, 16, v166
	v_lshlrev_b32_e32 v156, 16, v164
	s_waitcnt lgkmcnt(4)
	v_mfma_f32_16x16x32_bf16 v[94:97], v[140:143], v[64:67], v[94:97]
	ds_read_b64 v[140:141], v165 offset:768
	ds_read_b64 v[142:143], v165 offset:800
	v_pk_add_f32 v[174:175], v[156:157], v[158:159] neg_lo:[0,1] neg_hi:[0,1]
	v_add_u32_e32 v189, 49, v92
	s_waitcnt lgkmcnt(4)
	v_mfma_f32_16x16x32_bf16 v[94:97], v[98:101], v[68:71], v[94:97]
	ds_read_b64 v[98:99], v165 offset:832
	ds_read_b64 v[100:101], v165 offset:864
	s_add_i32 s60, s60, 1
	v_cmp_lt_u32_e32 vcc, s60, v109
	s_waitcnt lgkmcnt(2)
	v_mfma_f32_16x16x32_bf16 v[60:63], v[140:143], v[60:63], 0
	v_mfma_f32_16x16x32_bf16 v[156:159], v[160:163], v[84:87], v[94:97]
	ds_read_b64 v[160:161], v165 offset:896
	ds_read_b64 v[162:163], v165 offset:928
	ds_read_b64 v[166:167], v165 offset:992
	ds_read_b64 v[164:165], v165 offset:960
	s_nop 0
	v_lshlrev_b32_e32 v97, 16, v184
	s_waitcnt lgkmcnt(4)
	v_mfma_f32_16x16x32_bf16 v[60:63], v[98:101], v[64:67], v[60:63]
	v_lshlrev_b32_e32 v65, 16, v186
	v_lshlrev_b32_e32 v64, 16, v185
	v_lshlrev_b32_e32 v96, 16, v183
	s_waitcnt lgkmcnt(2)
	v_mfma_f32_16x16x32_bf16 v[60:63], v[160:163], v[68:71], v[60:63]
	v_add_f32_e64 v64, v64, -v158
	v_add_f32_e64 v65, v65, -v159
	v_mul_lo_u32 v159, v88, s24
	v_pk_add_f32 v[96:97], v[96:97], v[156:157] neg_lo:[0,1] neg_hi:[0,1]
	s_waitcnt lgkmcnt(0)
	v_mfma_f32_16x16x32_bf16 v[68:71], v[164:167], v[84:87], v[60:63]
	v_cvt_pk_bf16_f32 v66, v96, v97
	v_cvt_pk_bf16_f32 v67, v64, v65
	v_cvt_pk_bf16_f32 v65, v174, v175
	v_cvt_pk_bf16_f32 v60, v0, v1
	v_mov_b32_e32 v0, s1
	s_add_i32 s1, 16, 0x19200
	v_add_u32_e32 v158, s1, v90
	v_add_u32_e32 v84, v158, v159
	ds_read_b64 v[96:97], v84
	ds_read_b64 v[98:99], v84 offset:32
	ds_read_b32 v0, v0
	v_cvt_pk_bf16_f32 v61, v102, v103
	ds_read_b64 v[100:101], v84 offset:64
	ds_read_b64 v[102:103], v84 offset:96
	v_cvt_pk_bf16_f32 v63, v170, v171
	v_cvt_pk_bf16_f32 v62, v168, v169
	s_waitcnt lgkmcnt(2)
	v_mul_f32_e32 v157, 0x3fb8aa3b, v0
	v_lshlrev_b32_e32 v0, 6, v155
	v_lshl_add_u32 v155, v89, 4, s65
	ds_read_b128 v[140:143], v155
	v_ashrrev_i32_e32 v89, 31, v88
	v_lshl_add_u64 v[84:85], v[88:89], 2, v[116:117]
	v_mfma_f32_16x16x32_bf16 v[86:89], v[96:99], v[60:63], 0
	v_cvt_pk_bf16_f32 v64, v172, v173
	ds_read_b128 v[96:99], v155 offset:64
	s_waitcnt lgkmcnt(1)
	v_mul_f32_e32 v140, 0x3fb8aa3b, v140
	v_exp_f32_e32 v140, v140
	v_mfma_f32_16x16x32_bf16 v[86:89], v[100:103], v[64:67], v[86:89]
	v_sub_u32_e32 v100, 63, v92
	v_ashrrev_i32_e32 v1, 31, v0
	v_cndmask_b32_e64 v100, v100, v92, s[6:7]
	v_lshl_add_u64 v[0:1], v[0:1], 0, v[104:105]
	v_ashrrev_i32_e32 v101, 31, v100
	s_nop 2
	v_fma_f32 v72, v72, v140, v86
	v_lshl_add_u64 v[100:101], v[0:1], 0, v[100:101]
	v_mul_f32_e32 v86, 0x3fb8aa3b, v141
	v_lshlrev_b64 v[100:101], 12, v[100:101]
	v_exp_f32_e32 v86, v86
	v_lshl_add_u64 v[100:101], v[84:85], 0, v[100:101]
	global_store_dword v[100:101], v72, off
	v_sub_u32_e32 v72, 63, v176
	v_cndmask_b32_e64 v72, v72, v176, s[6:7]
	v_fma_f32 v86, v73, v86, v87
	v_ashrrev_i32_e32 v73, 31, v72
	v_lshl_add_u64 v[72:73], v[0:1], 0, v[72:73]
	v_lshlrev_b64 v[72:73], 12, v[72:73]
	v_lshl_add_u64 v[72:73], v[84:85], 0, v[72:73]
	v_mul_f32_e32 v87, 0x3fb8aa3b, v142
	global_store_dword v[72:73], v86, off
	v_sub_u32_e32 v72, 63, v177
	v_exp_f32_e32 v87, v87
	v_cndmask_b32_e64 v72, v72, v177, s[6:7]
	v_ashrrev_i32_e32 v73, 31, v72
	v_lshl_add_u64 v[72:73], v[0:1], 0, v[72:73]
	v_lshlrev_b64 v[72:73], 12, v[72:73]
	v_fma_f32 v74, v74, v87, v88
	v_lshl_add_u64 v[72:73], v[84:85], 0, v[72:73]
	v_add_u32_e32 v140, 0x900, v159
	global_store_dword v[72:73], v74, off
	v_mul_f32_e32 v72, 0x3fb8aa3b, v143
	v_add_u32_e32 v73, v158, v140
	v_exp_f32_e32 v72, v72
	ds_read_b64 v[100:101], v73
	ds_read_b64 v[102:103], v73 offset:32
	v_sub_u32_e32 v74, 63, v178
	v_cndmask_b32_e64 v86, v74, v178, s[6:7]
	v_fmac_f32_e32 v89, v75, v72
	ds_read_b64 v[74:75], v73 offset:96
	ds_read_b64 v[72:73], v73 offset:64
	v_ashrrev_i32_e32 v87, 31, v86
	v_lshl_add_u64 v[86:87], v[0:1], 0, v[86:87]
	s_waitcnt lgkmcnt(2)
	v_mfma_f32_16x16x32_bf16 v[100:103], v[100:103], v[60:63], 0
	v_lshlrev_b64 v[86:87], 12, v[86:87]
	v_lshl_add_u64 v[86:87], v[84:85], 0, v[86:87]
	global_store_dword v[86:87], v89, off
	v_mul_f32_e32 v86, 0x3fb8aa3b, v96
	v_exp_f32_e32 v87, v86
	s_waitcnt lgkmcnt(0)
	v_mfma_f32_16x16x32_bf16 v[72:75], v[72:75], v[64:67], v[100:103]
	v_sub_u32_e32 v86, 47, v92
	v_cndmask_b32_e64 v86, v86, v91, s[6:7]
	v_add_u32_e32 v141, 0x1200, v159
	ds_read_b128 v[100:103], v155 offset:128
	v_add_u32_e32 v94, 48, v92
	s_nop 2
	v_fma_f32 v72, v76, v87, v72
	v_ashrrev_i32_e32 v87, 31, v86
	v_lshl_add_u64 v[86:87], v[0:1], 0, v[86:87]
	v_mul_f32_e32 v76, 0x3fb8aa3b, v97
	v_lshlrev_b64 v[86:87], 12, v[86:87]
	v_exp_f32_e32 v76, v76
	v_lshl_add_u64 v[86:87], v[84:85], 0, v[86:87]
	global_store_dword v[86:87], v72, off
	v_sub_u32_e32 v72, 46, v92
	v_cndmask_b32_e64 v72, v72, v179, s[6:7]
	v_fma_f32 v76, v77, v76, v73
	v_ashrrev_i32_e32 v73, 31, v72
	v_lshl_add_u64 v[72:73], v[0:1], 0, v[72:73]
	v_lshlrev_b64 v[72:73], 12, v[72:73]
	v_lshl_add_u64 v[72:73], v[84:85], 0, v[72:73]
	v_mul_f32_e32 v77, 0x3fb8aa3b, v98
	global_store_dword v[72:73], v76, off
	v_sub_u32_e32 v72, 45, v92
	v_exp_f32_e32 v77, v77
	v_cndmask_b32_e64 v72, v72, v180, s[6:7]
	v_ashrrev_i32_e32 v73, 31, v72
	v_lshl_add_u64 v[72:73], v[0:1], 0, v[72:73]
	v_lshlrev_b64 v[72:73], 12, v[72:73]
	v_fma_f32 v74, v78, v77, v74
	v_lshl_add_u64 v[72:73], v[84:85], 0, v[72:73]
	global_store_dword v[72:73], v74, off
	v_add_u32_e32 v74, v158, v141
	v_mul_f32_e32 v73, 0x3fb8aa3b, v99
	ds_read_b64 v[86:87], v74
	ds_read_b64 v[88:89], v74 offset:32
	v_exp_f32_e32 v73, v73
	v_sub_u32_e32 v72, 44, v92
	v_cndmask_b32_e64 v72, v72, v181, s[6:7]
	ds_read_b64 v[96:97], v74 offset:64
	ds_read_b64 v[98:99], v74 offset:96
	v_fmac_f32_e32 v75, v79, v73
	v_ashrrev_i32_e32 v73, 31, v72
	v_lshl_add_u64 v[72:73], v[0:1], 0, v[72:73]
	v_lshlrev_b64 v[72:73], 12, v[72:73]
	v_lshl_add_u64 v[72:73], v[84:85], 0, v[72:73]
	global_store_dword v[72:73], v75, off
	s_waitcnt lgkmcnt(2)
	v_mfma_f32_16x16x32_bf16 v[72:75], v[86:89], v[60:63], 0
	ds_read_b128 v[76:79], v155 offset:192
	v_mul_f32_e32 v86, 0x3fb8aa3b, v100
	v_exp_f32_e32 v87, v86
	s_waitcnt lgkmcnt(1)
	v_mfma_f32_16x16x32_bf16 v[72:75], v[96:99], v[64:67], v[72:75]
	v_sub_u32_e32 v86, 31, v92
	v_cndmask_b32_e64 v86, v86, v93, s[6:7]
	v_add_u32_e32 v100, 0x1b00, v159
	v_add_u32_e32 v156, 50, v92
	v_add_u32_e32 v95, 51, v92
	s_nop 2
	v_fma_f32 v72, v80, v87, v72
	v_ashrrev_i32_e32 v87, 31, v86
	v_lshl_add_u64 v[86:87], v[0:1], 0, v[86:87]
	v_mul_f32_e32 v80, 0x3fb8aa3b, v101
	v_lshlrev_b64 v[86:87], 12, v[86:87]
	v_exp_f32_e32 v80, v80
	v_lshl_add_u64 v[86:87], v[84:85], 0, v[86:87]
	global_store_dword v[86:87], v72, off
	v_sub_u32_e32 v72, 30, v92
	v_cndmask_b32_e64 v72, v72, v182, s[6:7]
	v_fma_f32 v80, v81, v80, v73
	v_ashrrev_i32_e32 v73, 31, v72
	v_lshl_add_u64 v[72:73], v[0:1], 0, v[72:73]
	v_lshlrev_b64 v[72:73], 12, v[72:73]
	v_lshl_add_u64 v[72:73], v[84:85], 0, v[72:73]
	v_mul_f32_e32 v81, 0x3fb8aa3b, v102
	global_store_dword v[72:73], v80, off
	v_sub_u32_e32 v72, 29, v92
	v_exp_f32_e32 v81, v81
	v_cndmask_b32_e64 v72, v72, v187, s[6:7]
	v_ashrrev_i32_e32 v73, 31, v72
	v_lshl_add_u64 v[72:73], v[0:1], 0, v[72:73]
	v_lshlrev_b64 v[72:73], 12, v[72:73]
	v_fma_f32 v74, v82, v81, v74
	v_lshl_add_u64 v[72:73], v[84:85], 0, v[72:73]
	global_store_dword v[72:73], v74, off
	v_mul_f32_e32 v72, 0x3fb8aa3b, v103
	v_add_u32_e32 v74, v158, v100
	v_exp_f32_e32 v73, v72
	ds_read_b64 v[86:87], v74
	ds_read_b64 v[88:89], v74 offset:32
	v_sub_u32_e32 v72, 28, v92
	v_cndmask_b32_e64 v72, v72, v188, s[6:7]
	v_fmac_f32_e32 v75, v83, v73
	ds_read_b64 v[80:81], v74 offset:64
	ds_read_b64 v[82:83], v74 offset:96
	v_ashrrev_i32_e32 v73, 31, v72
	v_lshl_add_u64 v[72:73], v[0:1], 0, v[72:73]
	s_waitcnt lgkmcnt(2)
	v_mfma_f32_16x16x32_bf16 v[86:89], v[86:89], v[60:63], 0
	v_lshlrev_b64 v[72:73], 12, v[72:73]
	v_lshl_add_u64 v[72:73], v[84:85], 0, v[72:73]
	global_store_dword v[72:73], v75, off
	v_mul_f32_e32 v72, 0x3fb8aa3b, v76
	v_exp_f32_e32 v76, v72
	s_waitcnt lgkmcnt(0)
	v_mfma_f32_16x16x32_bf16 v[72:75], v[80:83], v[64:67], v[86:89]
	v_sub_u32_e32 v80, 15, v92
	v_cndmask_b32_e64 v80, v80, v94, s[6:7]
	v_ashrrev_i32_e32 v81, 31, v80
	v_lshl_add_u64 v[80:81], v[0:1], 0, v[80:81]
	v_lshlrev_b64 v[80:81], 12, v[80:81]
	s_nop 2
	v_fma_f32 v68, v68, v76, v72
	v_mul_f32_e32 v72, 0x3fb8aa3b, v77
	v_exp_f32_e32 v72, v72
	v_lshl_add_u64 v[80:81], v[84:85], 0, v[80:81]
	global_store_dword v[80:81], v68, off
	v_sub_u32_e32 v68, 14, v92
	v_cndmask_b32_e64 v68, v68, v189, s[6:7]
	v_fma_f32 v72, v69, v72, v73
	v_ashrrev_i32_e32 v69, 31, v68
	v_add_u32_e32 v101, s0, v159
	v_lshl_add_u64 v[68:69], v[0:1], 0, v[68:69]
	v_add_u32_e32 v73, v101, v90
	v_lshlrev_b64 v[68:69], 12, v[68:69]
	ds_read_b64 v[80:81], v73
	ds_read_b64 v[82:83], v73 offset:32
	v_lshl_add_u64 v[68:69], v[84:85], 0, v[68:69]
	global_store_dword v[68:69], v72, off
	v_sub_u32_e32 v69, 13, v92
	v_cndmask_b32_e64 v72, v69, v156, s[6:7]
	v_mul_f32_e32 v69, 0x3fb8aa3b, v78
	v_exp_f32_e32 v68, v157
	v_exp_f32_e32 v69, v69
	v_xor_b32_e32 v77, 8, v91
	v_pk_mul_f32 v[8:9], v[8:9], v[68:69] op_sel_hi:[1,0]
	v_pk_mul_f32 v[10:11], v[10:11], v[68:69] op_sel_hi:[1,0]
	v_fma_f32 v69, v70, v69, v74
	v_add_u32_e32 v70, s0, v141
	s_waitcnt lgkmcnt(0)
	v_mfma_f32_16x16x32_bf16 v[8:11], v[80:83], v[60:63], v[8:11]
	ds_read_b64 v[80:81], v73 offset:64
	ds_read_b64 v[82:83], v73 offset:96
	v_add_u32_e32 v73, s0, v140
	v_xad_u32 v76, v90, 16, v73
	v_lshl_add_u32 v77, v77, 1, v73
	ds_read_b64 v[86:87], v76
	ds_read_b64 v[88:89], v77
	v_xor_b32_e32 v76, 8, v93
	v_lshl_add_u32 v76, v76, 1, v73
	v_xor_b32_e32 v77, 8, v94
	v_lshl_add_u32 v73, v77, 1, v73
	ds_read_b64 v[96:97], v76
	ds_read_b64 v[98:99], v73
	v_xad_u32 v74, v90, 32, v70
	v_xor_b32_e32 v76, 16, v91
	s_waitcnt lgkmcnt(4)
	v_mfma_f32_16x16x32_bf16 v[8:11], v[80:83], v[64:67], v[8:11]
	v_lshl_add_u32 v76, v76, 1, v70
	ds_read_b64 v[80:81], v74
	ds_read_b64 v[82:83], v76
	v_xor_b32_e32 v74, 16, v93
	v_xor_b32_e32 v76, 16, v94
	v_pk_mul_f32 v[4:5], v[4:5], v[68:69] op_sel_hi:[1,0]
	v_pk_mul_f32 v[6:7], v[6:7], v[68:69] op_sel_hi:[1,0]
	v_lshl_add_u32 v74, v74, 1, v70
	v_lshl_add_u32 v70, v76, 1, v70
	s_waitcnt lgkmcnt(4)
	v_mfma_f32_16x16x32_bf16 v[4:7], v[86:89], v[60:63], v[4:7]
	v_ashrrev_i32_e32 v73, 31, v72
	ds_read_b64 v[86:87], v74
	ds_read_b64 v[88:89], v70
	v_add_u32_e32 v70, s0, v100
	v_lshl_add_u64 v[72:73], v[0:1], 0, v[72:73]
	v_pk_mul_f32 v[16:17], v[16:17], v[68:69] op_sel_hi:[1,0]
	v_pk_mul_f32 v[18:19], v[18:19], v[68:69] op_sel_hi:[1,0]
	v_xad_u32 v74, v90, 48, v70
	v_xor_b32_e32 v76, 24, v91
	v_lshlrev_b64 v[72:73], 12, v[72:73]
	s_waitcnt lgkmcnt(2)
	v_mfma_f32_16x16x32_bf16 v[16:19], v[80:83], v[60:63], v[16:19]
	v_lshl_add_u32 v76, v76, 1, v70
	ds_read_b64 v[80:81], v74
	ds_read_b64 v[82:83], v76
	v_xor_b32_e32 v74, 24, v93
	v_lshl_add_u32 v74, v74, 1, v70
	v_xor_b32_e32 v76, 24, v94
	v_lshl_add_u64 v[72:73], v[84:85], 0, v[72:73]
	v_mfma_f32_16x16x32_bf16 v[4:7], v[96:99], v[64:67], v[4:7]
	v_lshl_add_u32 v70, v76, 1, v70
	ds_read_b64 v[96:97], v74
	ds_read_b64 v[98:99], v70
	global_store_dword v[72:73], v69, off
	v_xad_u32 v72, v90, 64, v101
	v_xor_b32_e32 v73, 32, v91
	v_mul_f32_e32 v70, 0x3fb8aa3b, v79
	v_lshl_add_u32 v73, v73, 1, v101
	ds_read_b64 v[76:77], v72 offset:9216
	ds_read_b64 v[78:79], v73 offset:9216
	v_pk_mul_f32 v[12:13], v[12:13], v[68:69] op_sel_hi:[1,0]
	v_pk_mul_f32 v[14:15], v[14:15], v[68:69] op_sel_hi:[1,0]
	v_xor_b32_e32 v72, 32, v93
	v_xor_b32_e32 v73, 32, v94
	v_exp_f32_e32 v70, v70
	s_waitcnt lgkmcnt(4)
	v_mfma_f32_16x16x32_bf16 v[12:15], v[80:83], v[60:63], v[12:15]
	v_sub_u32_e32 v69, 12, v92
	v_lshl_add_u32 v72, v72, 1, v101
	v_lshl_add_u32 v73, v73, 1, v101
	s_movk_i32 s0, 0x50
	v_pk_mul_f32 v[24:25], v[24:25], v[68:69] op_sel_hi:[1,0]
	v_pk_mul_f32 v[26:27], v[26:27], v[68:69] op_sel_hi:[1,0]
	ds_read_b64 v[80:81], v72 offset:9216
	ds_read_b64 v[82:83], v73 offset:9216
	v_xad_u32 v72, v90, s0, v101
	v_xor_b32_e32 v73, 40, v91
	s_waitcnt lgkmcnt(2)
	v_mfma_f32_16x16x32_bf16 v[24:27], v[76:79], v[60:63], v[24:27]
	v_lshl_add_u32 v73, v73, 1, v101
	ds_read_b64 v[76:77], v72 offset:11520
	ds_read_b64 v[78:79], v73 offset:11520
	v_xor_b32_e32 v72, 40, v93
	v_lshl_add_u32 v72, v72, 1, v101
	v_xor_b32_e32 v73, 40, v94
	v_fmac_f32_e32 v75, v71, v70
	s_movk_i32 s0, 0x60
	v_xor_b32_e32 v70, 48, v91
	v_mfma_f32_16x16x32_bf16 v[16:19], v[86:89], v[64:67], v[16:19]
	v_lshl_add_u32 v73, v73, 1, v101
	ds_read_b64 v[86:87], v72 offset:11520
	ds_read_b64 v[88:89], v73 offset:11520
	v_pk_mul_f32 v[20:21], v[20:21], v[68:69] op_sel_hi:[1,0]
	v_mfma_f32_16x16x32_bf16 v[12:15], v[96:99], v[64:67], v[12:15]
	v_mul_f32_e64 v22, v22, v68
	v_mul_f32_e64 v23, v23, v68
	v_cndmask_b32_e64 v96, v69, v95, s[6:7]
	v_xad_u32 v69, v90, s0, v101
	v_lshl_add_u32 v72, v70, 1, v101
	ds_read_b64 v[70:71], v69 offset:13824
	ds_read_b64 v[72:73], v72 offset:13824
	v_pk_mul_f32 v[32:33], v[32:33], v[68:69] op_sel_hi:[1,0]
	v_pk_mul_f32 v[34:35], v[34:35], v[68:69] op_sel_hi:[1,0]
	v_xor_b32_e32 v69, 48, v93
	v_lshl_add_u32 v69, v69, 1, v101
	v_xor_b32_e32 v74, 48, v94
	s_waitcnt lgkmcnt(0)
	v_mfma_f32_16x16x32_bf16 v[32:35], v[70:73], v[60:63], v[32:35]
	s_movk_i32 s0, 0x70
	v_xor_b32_e32 v70, 56, v91
	v_lshl_add_u32 v74, v74, 1, v101
	v_mfma_f32_16x16x32_bf16 v[20:23], v[76:79], v[60:63], v[20:23]
	ds_read_b64 v[76:77], v69 offset:13824
	ds_read_b64 v[78:79], v74 offset:13824
	v_xad_u32 v69, v90, s0, v101
	v_lshl_add_u32 v72, v70, 1, v101
	ds_read_b64 v[70:71], v69 offset:16128
	ds_read_b64 v[72:73], v72 offset:16128
	v_xor_b32_e32 v69, 56, v93
	v_lshl_add_u32 v69, v69, 1, v101
	v_xor_b32_e32 v74, 56, v94
	v_mfma_f32_16x16x32_bf16 v[24:27], v[80:83], v[64:67], v[24:27]
	v_lshl_add_u32 v74, v74, 1, v101
	ds_read_b64 v[80:81], v69 offset:16128
	ds_read_b64 v[82:83], v74 offset:16128
	v_pk_mul_f32 v[28:29], v[28:29], v[68:69] op_sel_hi:[1,0]
	v_pk_mul_f32 v[30:31], v[30:31], v[68:69] op_sel_hi:[1,0]
	v_ashrrev_i32_e32 v97, 31, v96
	v_mfma_f32_16x16x32_bf16 v[20:23], v[86:89], v[64:67], v[20:23]
	v_lshl_add_u64 v[0:1], v[0:1], 0, v[96:97]
	v_lshlrev_b64 v[0:1], 12, v[0:1]
	v_lshl_add_u64 v[0:1], v[84:85], 0, v[0:1]
	s_waitcnt lgkmcnt(2)
	v_mfma_f32_16x16x32_bf16 v[28:31], v[70:73], v[60:63], v[28:31]
	global_store_dword v[0:1], v75, off
	v_mfma_f32_16x16x32_bf16 v[32:35], v[76:79], v[64:67], v[32:35]
	s_waitcnt lgkmcnt(0)
	v_mfma_f32_16x16x32_bf16 v[28:31], v[80:83], v[64:67], v[28:31]
	s_and_saveexec_b64 s[0:1], vcc
	s_cbranch_execz .LBB0_644
	v_and_b32_e32 v0, 7, v3
	v_ashrrev_i32_e32 v1, 3, v3
	v_cmp_eq_u32_e32 vcc, 0, v0
	s_and_saveexec_b64 s[12:13], vcc
	s_cbranch_execz .LBB0_643
	s_and_b64 s[66:67], s[14:15], exec
	s_cselect_b32 s66, s55, s64
	s_add_i32 s67, 16, 0x1c900
	s_add_i32 vcc_lo, 16, 0x25900
	s_and_b64 s[64:65], s[14:15], exec
	s_cselect_b32 s64, vcc_lo, s67
	v_lshlrev_b32_e32 v3, 2, v1
	v_add_u32_e32 v60, s64, v3
	v_add_u32_e32 v3, s66, v3
	s_waitcnt vmcnt(17)
	ds_write_b32 v3, v122
	ds_write_b32 v60, v110
	s_branch .LBB0_643

.LBB0_720:
	s_or_b64 exec, exec, s[10:11]
	s_and_b32 s13, 1, s12
	s_cselect_b32 s10, 0, 0x8c00
	s_add_i32 s10, s10, 16
	v_add3_u32 v114, s10, v158, v105
	ds_read_b128 v[118:121], v114
	ds_read_b128 v[122:125], v114 offset:64
	ds_read_b128 v[126:129], v114 offset:4352
	ds_read_b128 v[130:133], v114 offset:4416
	s_waitcnt lgkmcnt(3)
	v_mfma_f32_16x16x32_bf16 v[118:121], v[118:121], v[36:39], 0
	s_waitcnt lgkmcnt(1)
	v_mfma_f32_16x16x32_bf16 v[126:129], v[126:129], v[36:39], 0
	s_nop 0
	v_mfma_f32_16x16x32_bf16 v[118:121], v[122:125], v[40:43], v[118:121]
	ds_read_b128 v[122:125], v114 offset:8704
	s_waitcnt lgkmcnt(1)
	v_mfma_f32_16x16x32_bf16 v[126:129], v[130:133], v[40:43], v[126:129]
	ds_read_b128 v[130:133], v114 offset:8768
	ds_read_b128 v[138:141], v114 offset:13056
	ds_read_b128 v[160:163], v114 offset:13120
	s_waitcnt lgkmcnt(3)
	v_mfma_f32_16x16x32_bf16 v[122:125], v[122:125], v[36:39], 0
	s_waitcnt lgkmcnt(2)
	v_mfma_f32_16x16x32_bf16 v[130:133], v[130:133], v[40:43], v[122:125]
	s_nop 5
	v_max3_f32 v122, v118, s26, v119
	v_max3_f32 v122, v122, v120, v121
	v_max3_f32 v134, v122, v126, v127
	s_waitcnt lgkmcnt(1)
	v_mfma_f32_16x16x32_bf16 v[122:125], v[138:141], v[36:39], 0
	v_max3_f32 v134, v134, v128, v129
	v_max3_f32 v134, v134, v130, v131
	v_max3_f32 v134, v134, v132, v133
	s_waitcnt lgkmcnt(0)
	v_mfma_f32_16x16x32_bf16 v[138:141], v[160:163], v[40:43], v[122:125]
	s_nop 7
	v_max3_f32 v122, v134, v138, v139
	v_max3_f32 v122, v122, v140, v141
	v_mul_f32_e32 v134, 0x3e38aa3b, v122
	v_mul_f32_e32 v135, 0x3e38aa3b, v122
	ds_read_b128 v[122:125], v114 offset:128
	ds_read_b128 v[166:169], v114 offset:192
	ds_read_b128 v[170:173], v114 offset:4544
	s_nop 0
	v_permlane16_swap_b32_e32 v134, v135
	v_max_f32_e32 v134, v134, v135
	v_mov_b32_e32 v135, v134
	s_nop 1
	v_permlane32_swap_b32_e32 v134, v135
	s_waitcnt lgkmcnt(2)
	v_mfma_f32_16x16x32_bf16 v[122:125], v[122:125], v[48:51], 0
	v_max3_f32 v159, v117, v134, v135
	v_sub_f32_e32 v134, v117, v159
	v_fma_f32 v117, v118, s27, -v159
	v_fma_f32 v118, v119, s27, -v159
	v_fma_f32 v119, v120, s27, -v159
	v_fma_f32 v120, v121, s27, -v159
	v_exp_f32_e32 v162, v118
	v_exp_f32_e32 v163, v119
	v_exp_f32_e32 v164, v120
	ds_read_b128 v[118:121], v114 offset:4480
	s_waitcnt lgkmcnt(2)
	v_mfma_f32_16x16x32_bf16 v[174:177], v[166:169], v[52:55], v[122:125]
	v_exp_f32_e32 v161, v117
	v_fma_f32 v117, v126, s27, -v159
	v_exp_f32_e32 v165, v117
	ds_read_b128 v[122:125], v114 offset:8832
	s_waitcnt lgkmcnt(1)
	v_mfma_f32_16x16x32_bf16 v[118:121], v[118:121], v[48:51], 0
	v_fma_f32 v117, v127, s27, -v159
	v_exp_f32_e32 v166, v117
	v_fma_f32 v117, v128, s27, -v159
	v_fma_f32 v135, v129, s27, -v159
	ds_read_b128 v[126:129], v114 offset:8896
	v_mfma_f32_16x16x32_bf16 v[178:181], v[170:173], v[52:55], v[118:121]
	ds_read_b128 v[168:171], v114 offset:13184
	ds_read_b128 v[182:185], v114 offset:13248
	v_fma_f32 v114, v132, s27, -v159
	s_waitcnt lgkmcnt(3)
	v_mfma_f32_16x16x32_bf16 v[122:125], v[122:125], v[48:51], 0
	v_fma_f32 v118, v130, s27, -v159
	v_exp_f32_e32 v121, v118
	v_fma_f32 v118, v131, s27, -v159
	s_waitcnt lgkmcnt(2)
	v_mfma_f32_16x16x32_bf16 v[186:189], v[126:129], v[52:55], v[122:125]
	v_exp_f32_e32 v119, v135
	v_exp_f32_e32 v136, v134
	v_exp_f32_e32 v117, v117
	s_waitcnt lgkmcnt(1)
	v_mfma_f32_16x16x32_bf16 v[128:131], v[168:171], v[48:51], 0
	v_exp_f32_e32 v123, v118
	v_max3_f32 v118, v174, s26, v175
	v_max3_f32 v118, v118, v176, v177
	s_waitcnt lgkmcnt(0)
	v_mfma_f32_16x16x32_bf16 v[182:185], v[182:185], v[52:55], v[128:131]
	v_max3_f32 v118, v118, v178, v179
	v_max3_f32 v118, v118, v180, v181
	v_max3_f32 v118, v118, v186, v187
	v_max3_f32 v118, v118, v188, v189
	v_exp_f32_e32 v125, v114
	s_nop 2
	v_max3_f32 v118, v118, v182, v183
	v_max3_f32 v118, v118, v184, v185
	v_mul_f32_e32 v118, 0x3e38aa3b, v118
	v_fma_f32 v114, v133, s27, -v159
	v_mov_b32_e32 v120, v118
	v_exp_f32_e32 v127, v114
	v_fma_f32 v114, v138, s27, -v159
	v_permlane16_swap_b32_e32 v118, v120
	v_exp_f32_e32 v129, v114
	v_max_f32_e32 v118, v118, v120
	v_fma_f32 v114, v139, s27, -v159
	v_mov_b32_e32 v120, v118
	v_exp_f32_e32 v131, v114
	v_fma_f32 v114, v140, s27, -v159
	v_permlane32_swap_b32_e32 v118, v120
	v_exp_f32_e32 v133, v114
	v_fma_f32 v114, v141, s27, -v159
	v_max3_f32 v160, v116, v118, v120
	v_exp_f32_e32 v135, v114
	v_sub_f32_e32 v114, v116, v160
	v_fma_f32 v116, v174, s27, -v160
	v_exp_f32_e32 v167, v116
	v_fma_f32 v116, v175, s27, -v160
	v_exp_f32_e32 v168, v116
	v_fma_f32 v116, v176, s27, -v160
	v_exp_f32_e32 v169, v116
	v_fma_f32 v116, v177, s27, -v160
	v_exp_f32_e32 v138, v114
	v_lshlrev_b32_e32 v114, 1, v3
	v_exp_f32_e32 v170, v116
	v_fma_f32 v116, v178, s27, -v160
	v_add3_u32 v139, s10, v115, v114
	v_add3_u32 v178, s10, v152, v114
	v_add_u32_e32 v173, 0x4000, v139
	v_add_u32_e32 v190, 0x4000, v178
	v_fma_f32 v128, v182, s27, -v160
	v_fma_f32 v130, v183, s27, -v160
	v_fma_f32 v132, v184, s27, -v160
	v_fma_f32 v134, v185, s27, -v160
	ds_read_b64 v[174:175], v173 offset:1024
	ds_read_b64 v[176:177], v173 offset:1056
	ds_read_b64 v[182:183], v190 offset:1024
	ds_read_b64 v[184:185], v190 offset:1056
	v_exp_f32_e32 v171, v116
	v_fma_f32 v116, v179, s27, -v160
	v_exp_f32_e32 v172, v116
	v_fma_f32 v116, v180, s27, -v160
	v_fma_f32 v118, v181, s27, -v160
	v_exp_f32_e32 v116, v116
	v_exp_f32_e32 v118, v118
	v_pk_mul_f32 v[98:99], v[98:99], v[136:137] op_sel_hi:[1,0]
	v_pk_mul_f32 v[96:97], v[96:97], v[136:137] op_sel_hi:[1,0]
	v_pk_mul_f32 v[94:95], v[94:95], v[136:137] op_sel_hi:[1,0]
	v_pk_mul_f32 v[92:93], v[92:93], v[136:137] op_sel_hi:[1,0]
	v_cvt_pk_bf16_f32 v143, v117, v119
	v_cvt_pk_bf16_f32 v142, v165, v166
	v_cvt_pk_bf16_f32 v141, v163, v164
	v_cvt_pk_bf16_f32 v140, v161, v162
	v_pk_mul_f32 v[82:83], v[82:83], v[138:139] op_sel_hi:[1,0]
	v_pk_mul_f32 v[80:81], v[80:81], v[138:139] op_sel_hi:[1,0]
	v_cvt_pk_bf16_f32 v181, v116, v118
	v_cvt_pk_bf16_f32 v180, v171, v172
	v_cvt_pk_bf16_f32 v179, v169, v170
	v_cvt_pk_bf16_f32 v178, v167, v168
	v_pk_mul_f32 v[70:71], v[70:71], v[138:139] op_sel_hi:[1,0]
	v_pk_mul_f32 v[68:69], v[68:69], v[138:139] op_sel_hi:[1,0]
	s_waitcnt lgkmcnt(2)
	v_mfma_f32_16x16x32_bf16 v[96:99], v[174:177], v[140:143], v[96:99]
	v_mul_f32_e64 v78, v78, v136
	v_mul_f32_e64 v79, v79, v136
	v_pk_mul_f32 v[76:77], v[76:77], v[136:137] op_sel_hi:[1,0]
	v_pk_mul_f32 v[74:75], v[74:75], v[136:137] op_sel_hi:[1,0]
	v_mfma_f32_16x16x32_bf16 v[80:83], v[174:177], v[178:181], v[80:83]
	v_add3_u32 v174, s10, v153, v114
	v_add_u32_e32 v191, 0x4000, v174
	ds_read_b64 v[174:175], v191 offset:1024
	ds_read_b64 v[176:177], v191 offset:1056
	s_waitcnt lgkmcnt(2)
	v_mfma_f32_16x16x32_bf16 v[92:95], v[182:185], v[140:143], v[92:95]
	v_mul_f32_e64 v58, v58, v138
	v_mul_f32_e64 v59, v59, v138
	v_pk_mul_f32 v[56:57], v[56:57], v[138:139] op_sel_hi:[1,0]
	v_pk_mul_f32 v[72:73], v[72:73], v[136:137] op_sel_hi:[1,0]
	v_mfma_f32_16x16x32_bf16 v[68:71], v[182:185], v[178:181], v[68:71]
	v_add3_u32 v182, s10, v154, v114
	v_add_u32_e32 v192, 0x4000, v182
	ds_read_b64 v[182:183], v192 offset:1024
	ds_read_b64 v[184:185], v192 offset:1056
	v_add_u32_e32 v193, 0x6800, v139
	v_pk_mul_f32 v[26:27], v[26:27], v[138:139] op_sel_hi:[1,0]
	v_pk_mul_f32 v[24:25], v[24:25], v[138:139] op_sel_hi:[1,0]
	v_add_u32_e32 v194, 0x7000, v139
	s_waitcnt lgkmcnt(2)
	v_mfma_f32_16x16x32_bf16 v[76:79], v[174:177], v[140:143], v[76:79]
	v_mul_f32_e64 v62, v62, v136
	v_mul_f32_e64 v63, v63, v136
	v_pk_mul_f32 v[60:61], v[60:61], v[136:137] op_sel_hi:[1,0]
	v_pk_mul_f32 v[30:31], v[30:31], v[136:137] op_sel_hi:[1,0]
	v_mfma_f32_16x16x32_bf16 v[56:59], v[174:177], v[178:181], v[56:59]
	ds_read_b64 v[174:175], v193
	ds_read_b64 v[176:177], v193 offset:32
	v_pk_mul_f32 v[66:67], v[66:67], v[138:139] op_sel_hi:[1,0]
	v_pk_mul_f32 v[64:65], v[64:65], v[138:139] op_sel_hi:[1,0]
	s_waitcnt lgkmcnt(2)
	v_mfma_f32_16x16x32_bf16 v[72:75], v[182:185], v[140:143], v[72:75]
	v_mul_f32_e64 v28, v28, v136
	v_mul_f32_e64 v29, v29, v136
	v_add_u32_e32 v195, 0x7800, v139
	v_pk_mul_f32 v[46:47], v[46:47], v[138:139] op_sel_hi:[1,0]
	v_mfma_f32_16x16x32_bf16 v[24:27], v[182:185], v[178:181], v[24:27]
	ds_read_b64 v[182:183], v194 offset:256
	ds_read_b64 v[184:185], v194 offset:288
	v_pk_mul_f32 v[44:45], v[44:45], v[138:139] op_sel_hi:[1,0]
	v_add_u32_e32 v139, 0x8000, v139
	s_waitcnt lgkmcnt(2)
	v_mfma_f32_16x16x32_bf16 v[60:63], v[174:177], v[140:143], v[60:63]
	v_mul_f32_e64 v34, v34, v138
	v_mul_f32_e64 v35, v35, v138
	v_pk_mul_f32 v[32:33], v[32:33], v[138:139] op_sel_hi:[1,0]
	v_pk_mul_f32 v[90:91], v[90:91], v[138:139] op_sel_hi:[1,0]
	v_mfma_f32_16x16x32_bf16 v[64:67], v[174:177], v[178:181], v[64:67]
	ds_read_b64 v[174:175], v195 offset:512
	ds_read_b64 v[176:177], v195 offset:544
	v_pk_mul_f32 v[88:89], v[88:89], v[138:139] op_sel_hi:[1,0]
	v_fma_f32 v120, v186, s27, -v160
	s_waitcnt lgkmcnt(2)
	v_mfma_f32_16x16x32_bf16 v[28:31], v[182:185], v[140:143], v[28:31]
	v_fma_f32 v122, v187, s27, -v160
	v_fma_f32 v124, v188, s27, -v160
	v_fma_f32 v126, v189, s27, -v160
	v_mfma_f32_16x16x32_bf16 v[44:47], v[182:185], v[178:181], v[44:47]
	ds_read_b64 v[182:183], v139 offset:768
	ds_read_b64 v[184:185], v139 offset:800
	v_exp_f32_e32 v120, v120
	v_exp_f32_e32 v122, v122
	s_waitcnt lgkmcnt(2)
	v_mfma_f32_16x16x32_bf16 v[32:35], v[174:177], v[178:181], v[32:35]
	v_exp_f32_e32 v124, v124
	v_exp_f32_e32 v126, v126
	v_exp_f32_e32 v128, v128
	s_waitcnt lgkmcnt(0)
	v_mfma_f32_16x16x32_bf16 v[88:91], v[182:185], v[178:181], v[88:91]
	ds_read_b64 v[178:179], v190 offset:1088
	ds_read_b64 v[180:181], v190 offset:1120
	v_exp_f32_e32 v130, v130
	v_exp_f32_e32 v132, v132
	v_exp_f32_e32 v134, v134
	v_pk_mul_f32 v[22:23], v[22:23], v[136:137] op_sel_hi:[1,0]
	v_pk_mul_f32 v[20:21], v[20:21], v[136:137] op_sel_hi:[1,0]
	v_pk_mul_f32 v[86:87], v[86:87], v[136:137] op_sel_hi:[1,0]
	v_pk_mul_f32 v[84:85], v[84:85], v[136:137] op_sel_hi:[1,0]
	v_mfma_f32_16x16x32_bf16 v[20:23], v[174:177], v[140:143], v[20:23]
	v_cvt_pk_bf16_f32 v177, v133, v135
	v_cvt_pk_bf16_f32 v176, v129, v131
	v_cvt_pk_bf16_f32 v175, v125, v127
	v_mfma_f32_16x16x32_bf16 v[84:87], v[182:185], v[140:143], v[84:87]
	v_cvt_pk_bf16_f32 v174, v121, v123
	v_cvt_pk_bf16_f32 v143, v132, v134
	v_cvt_pk_bf16_f32 v142, v128, v130
	v_cvt_pk_bf16_f32 v141, v124, v126
	v_cvt_pk_bf16_f32 v140, v120, v122
	s_waitcnt lgkmcnt(0)
	v_mfma_f32_16x16x32_bf16 v[92:95], v[178:181], v[174:177], v[92:95]
	ds_read_b64 v[186:187], v173 offset:1088
	ds_read_b64 v[188:189], v173 offset:1120
	v_mfma_f32_16x16x32_bf16 v[68:71], v[178:181], v[140:143], v[68:71]
	ds_read_b64 v[178:179], v191 offset:1088
	ds_read_b64 v[180:181], v191 offset:1120
	s_waitcnt lgkmcnt(0)
	v_mfma_f32_16x16x32_bf16 v[76:79], v[178:181], v[174:177], v[76:79]
	v_mfma_f32_16x16x32_bf16 v[56:59], v[178:181], v[140:143], v[56:59]
	ds_read_b64 v[178:179], v192 offset:1088
	ds_read_b64 v[180:181], v192 offset:1120
	s_waitcnt lgkmcnt(0)
	v_mfma_f32_16x16x32_bf16 v[72:75], v[178:181], v[174:177], v[72:75]
	v_mfma_f32_16x16x32_bf16 v[24:27], v[178:181], v[140:143], v[24:27]
	ds_read_b64 v[178:179], v193 offset:64
	ds_read_b64 v[180:181], v193 offset:96
	s_waitcnt lgkmcnt(0)
	v_mfma_f32_16x16x32_bf16 v[60:63], v[178:181], v[174:177], v[60:63]
	v_mfma_f32_16x16x32_bf16 v[64:67], v[178:181], v[140:143], v[64:67]
	ds_read_b64 v[178:179], v194 offset:320
	ds_read_b64 v[180:181], v194 offset:352
	s_waitcnt lgkmcnt(0)
	v_mfma_f32_16x16x32_bf16 v[28:31], v[178:181], v[174:177], v[28:31]
	v_mfma_f32_16x16x32_bf16 v[44:47], v[178:181], v[140:143], v[44:47]
	ds_read_b64 v[178:179], v195 offset:576
	ds_read_b64 v[180:181], v195 offset:608
	s_waitcnt lgkmcnt(0)
	v_mfma_f32_16x16x32_bf16 v[20:23], v[178:181], v[174:177], v[20:23]
	v_mfma_f32_16x16x32_bf16 v[32:35], v[178:181], v[140:143], v[32:35]
	ds_read_b64 v[178:179], v139 offset:832
	ds_read_b64 v[180:181], v139 offset:864
	v_mfma_f32_16x16x32_bf16 v[96:99], v[186:189], v[174:177], v[96:99]
	v_mfma_f32_16x16x32_bf16 v[80:83], v[186:189], v[140:143], v[80:83]
	s_waitcnt lgkmcnt(0)
	v_mfma_f32_16x16x32_bf16 v[84:87], v[178:181], v[174:177], v[84:87]
	v_mfma_f32_16x16x32_bf16 v[88:91], v[178:181], v[140:143], v[88:91]
	s_and_saveexec_b64 s[10:11], s[6:7]
	s_cbranch_execz .LBB0_717
	s_cmp_eq_u32 s13, 1
	s_cselect_b32 s6, 0x8c00, 0
	s_add_i32 s6, s6, 16
	v_add3_u32 v139, s6, v155, v102
	s_waitcnt vmcnt(0)
	ds_write_b128 v139, v[4:7]
	ds_write_b128 v139, v[8:11] offset:8704
	v_add3_u32 v139, s6, v156, v104
	ds_write_b128 v139, v[12:15] offset:17408
	ds_write_b128 v139, v[16:19] offset:26624
	s_branch .LBB0_717
